# RWKV producer pre-loop wy_issue: bf16 al loads go straight to their final registers, eight prologue vmcnt(0) waits replaced by one wait plus in-place shifts
# baseline (speedup 1.0000x reference)
; #define LAS __attribute__((address_space(3)))
; __device__ __forceinline__ float bf2f(unsigned h) { return __uint_as_float(h << 16); }
; __device__ __forceinline__ void wy_issue(const Args& a, LAS unsigned char* stg, int b, int h, int c, int lane, float (&dec)[WY_T], float (&al)[WY_T], float (&rn)[WY_T]) {
;     ...
;     const size_t tok0 = (size_t)b * SEQ + (size_t)c * WY_T; const int ch = h * 64 + lane;
; #pragma unroll
;     for (int j = 0; j < 7; ++j) { const int idx = j * 64 + lane;
;         if (idx < 408) { const int row = idx >> 3, trel = row / 3, vec = row - 3 * trel; size_t tk = tok0 + trel; tk = (tk == 0) ? 1 : tk;
;             __builtin_amdgcn_global_load_lds((const unsigned*)(PR + (tk - 1) * 1792 + vec * 512 + h * 64 + (idx & 7) * 8), (LAS unsigned*)(stg + j * 1024), 16, 0, 0); } }
; #pragma unroll
;     for (int t = 0; t < WY_T; ++t) { dec[t] = DEC[(tok0 + t) * 512 + ch]; al[t] = bf2f(AL[(tok0 + t) * 512 + ch]); rn[t] = CT[(tok0 + t) * 8 + h]; }
.LBB0_1419:
	s_or_b64 exec, exec, s[0:1]
	s_cmpk_gt_u32 s90, 0x1ff
	s_cbranch_scc1 .LBB0_1382
	s_mul_i32 s0, s69, 0x4500
	s_add_i32 s89, s0, 0
	s_lshl_b32 s0, s4, 2
	v_readlane_b32 s2, v239, 62
	v_readlane_b32 s3, v239, 63
	s_add_u32 s91, s2, s0
	s_addc_u32 s68, s3, 0
	s_or_b32 s44, s92, 14
	s_mov_b32 s45, s93
	s_lshl_b64 s[0:1], s[44:45], 5
	s_add_u32 s0, s91, s0
	s_addc_u32 s1, s68, s1
	s_or_b32 s2, s92, 15
	s_mov_b32 s3, s93
	global_load_dword v36, v119, s[0:1]
	s_lshl_b64 s[0:1], s[2:3], 5
	s_add_u32 s0, s91, s0
	s_addc_u32 s1, s68, s1
	s_mov_b32 s81, s94
	v_or_b32_e32 v24, s80, v113
	global_load_dword v37, v119, s[0:1]
	s_lshl_b64 s[0:1], s[92:93], 9
	s_or_b32 s94, s92, 1
	s_mov_b32 s95, s93
	v_or_b32_e32 v0, s0, v24
	v_mov_b32_e32 v1, s1
	s_lshl_b64 s[0:1], s[94:95], 9
	v_or_b32_e32 v2, s0, v24
	v_mov_b32_e32 v3, s1
	v_lshl_add_u64 v[4:5], v[0:1], 1, s[60:61]
	v_lshl_add_u64 v[6:7], v[2:3], 1, s[60:61]
	global_load_ushort v27, v[6:7], off
	s_nop 0
	global_load_ushort v26, v[4:5], off
	s_or_b32 s96, s92, 2
	s_mov_b32 s97, s93
	s_lshl_b64 s[0:1], s[96:97], 9
	s_or_b32 vcc_lo, s92, 3
	s_mov_b32 vcc_hi, s93
	v_mov_b32_e32 v5, s1
	s_or_b32 s52, s92, 4
	s_mov_b32 s53, s93
	s_or_b32 s56, s92, 5
	s_mov_b32 s57, s93
	s_or_b32 s72, s92, 7
	s_mov_b32 s73, s93
	s_or_b32 s30, s92, 8
	s_mov_b32 s31, s93
	s_or_b32 s36, s92, 9
	s_mov_b32 s37, s93
	s_or_b32 s38, s92, 10
	s_mov_b32 s39, s93
	s_or_b32 s40, s92, 11
	s_mov_b32 s41, s93
	s_lshl_b64 s[2:3], s[2:3], 9
	s_lshl_b64 s[44:45], s[44:45], 9
	v_or_b32_e32 v46, s2, v24
	v_mov_b32_e32 v47, s3
	v_lshl_add_u64 v[48:49], v[46:47], 1, s[60:61]
	v_lshl_add_u64 v[0:1], v[0:1], 2, s[50:51]
	v_lshl_add_u64 v[2:3], v[2:3], 2, s[50:51]
	v_add_u32_e32 v79, s89, v198
	v_add_u32_e32 v83, s89, v221
	v_add_u32_e32 v229, s89, v201
	v_add_u32_e32 v230, s89, v202
	v_add_u32_e32 v231, s89, v203
	v_add_u32_e32 v232, s89, v204
	v_or_b32_e32 v4, s0, v24
	s_lshl_b64 s[0:1], vcc, 9
	v_or_b32_e32 v6, s0, v24
	v_mov_b32_e32 v7, s1
	v_lshl_add_u64 v[8:9], v[4:5], 1, s[60:61]
	v_lshl_add_u64 v[10:11], v[6:7], 1, s[60:61]
	global_load_ushort v29, v[10:11], off
	s_nop 0
	global_load_ushort v28, v[8:9], off
	s_lshl_b64 s[0:1], s[52:53], 9
	v_mov_b32_e32 v9, s1
	v_or_b32_e32 v8, s0, v24
	s_lshl_b64 s[0:1], s[56:57], 9
	v_or_b32_e32 v10, s0, v24
	v_mov_b32_e32 v11, s1
	v_lshl_add_u64 v[12:13], v[8:9], 1, s[60:61]
	v_lshl_add_u64 v[14:15], v[10:11], 1, s[60:61]
	global_load_ushort v31, v[14:15], off
	s_nop 0
	global_load_ushort v30, v[12:13], off
	s_or_b32 s0, s92, 6
	s_mov_b32 s1, s93
	s_lshl_b64 s[4:5], s[0:1], 9
	v_mov_b32_e32 v13, s5
	v_or_b32_e32 v12, s4, v24
	s_lshl_b64 s[4:5], s[72:73], 9
	v_or_b32_e32 v14, s4, v24
	v_mov_b32_e32 v15, s5
	v_lshl_add_u64 v[16:17], v[12:13], 1, s[60:61]
	v_lshl_add_u64 v[18:19], v[14:15], 1, s[60:61]
	global_load_ushort v33, v[18:19], off
	s_nop 0
	global_load_ushort v32, v[16:17], off
	s_lshl_b64 s[4:5], s[30:31], 9
	v_mov_b32_e32 v17, s5
	v_or_b32_e32 v16, s4, v24
	s_lshl_b64 s[4:5], s[36:37], 9
	v_or_b32_e32 v18, s4, v24
	v_mov_b32_e32 v19, s5
	v_lshl_add_u64 v[20:21], v[16:17], 1, s[60:61]
	v_lshl_add_u64 v[22:23], v[18:19], 1, s[60:61]
	global_load_ushort v35, v[22:23], off
	s_nop 0
	global_load_ushort v34, v[20:21], off
	s_lshl_b64 s[4:5], s[38:39], 9
	v_mov_b32_e32 v21, s5
	v_or_b32_e32 v20, s4, v24
	s_lshl_b64 s[4:5], s[40:41], 9
	v_or_b32_e32 v22, s4, v24
	v_mov_b32_e32 v23, s5
	v_lshl_add_u64 v[38:39], v[20:21], 1, s[60:61]
	v_lshl_add_u64 v[40:41], v[22:23], 1, s[60:61]
	global_load_ushort v59, v[40:41], off
	s_nop 0
	global_load_ushort v58, v[38:39], off
	s_or_b32 s4, s92, 12
	s_mov_b32 s5, s93
	s_lshl_b64 s[34:35], s[4:5], 9
	v_mov_b32_e32 v39, s35
	s_mov_b32 s35, s93
	s_lshl_b64 s[2:3], s[4:5], 5
	v_readlane_b32 s4, v239, 38
	v_readlane_b32 s5, v239, 39
	v_readlane_b32 s16, v239, 50
	v_readlane_b32 s17, v239, 51
	v_readlane_b32 s18, v239, 52
	v_readlane_b32 s19, v239, 53
	v_readlane_b32 s6, v239, 40
	v_readlane_b32 s7, v239, 41
	v_readlane_b32 s8, v239, 42
	v_readlane_b32 s9, v239, 43
	v_readlane_b32 s10, v239, 44
	v_readlane_b32 s11, v239, 45
	v_readlane_b32 s12, v239, 46
	v_readlane_b32 s13, v239, 47
	v_readlane_b32 s14, v239, 48
	v_readlane_b32 s15, v239, 49
	v_or_b32_e32 v38, s34, v24
	s_or_b32 s34, s92, 13
	s_lshl_b64 s[82:83], s[34:35], 9
	v_or_b32_e32 v42, s82, v24
	v_mov_b32_e32 v43, s83
	v_lshl_add_u64 v[40:41], v[38:39], 1, s[60:61]
	v_lshl_add_u64 v[44:45], v[42:43], 1, s[60:61]
	global_load_ushort v65, v[44:45], off
	s_nop 0
	global_load_ushort v64, v[40:41], off
	v_mov_b32_e32 v41, s45
	s_add_u32 s2, s91, s2
; __device__ __forceinline__ float bf2f(unsigned h) { return __uint_as_float(h << 16); }
; __device__ __forceinline__ void wy_issue(const Args& a, LAS unsigned char* stg, int b, int h, int c, int lane, float (&dec)[WY_T], float (&al)[WY_T], float (&rn)[WY_T]) {
;     ...
;     for (int t = 0; t < WY_T; ++t) { dec[t] = DEC[(tok0 + t) * 512 + ch]; al[t] = bf2f(AL[(tok0 + t) * 512 + ch]); rn[t] = CT[(tok0 + t) * 8 + h]; }
; }
; __device__ __forceinline__ void wy_build1(const Args& a, LAS unsigned char* slot, const LAS unsigned char* stg, int h, int c, int lane, const float (&dec)[WY_T], const float (&alr)[WY_T], const float (&rn)[WY_T]) {
;     ...
;     const float mixr = ((const float*)a.in[16])[ch], mixk = ((const float*)a.in[16])[512 + ch], mixv = ((const float*)a.in[16])[1024 + ch];
;     const float k_k = ((const float*)a.in[22])[ch], k_a = ((const float*)a.in[23])[ch];
	s_addc_u32 s3, s68, s3
	v_or_b32_e32 v40, s44, v24
	v_lshl_add_u64 v[44:45], v[40:41], 1, s[60:61]
	global_load_ushort v77, v[48:49], off
	s_nop 0
	global_load_ushort v76, v[44:45], off
	global_load_dword v74, v119, s[2:3]
	s_lshl_b64 s[2:3], s[34:35], 5
	s_add_u32 s2, s91, s2
	s_addc_u32 s3, s68, s3
	global_load_dword v75, v119, s[2:3]
	s_lshl_b64 s[2:3], s[38:39], 5
	s_add_u32 s2, s91, s2
	s_addc_u32 s3, s68, s3
	global_load_dword v72, v119, s[2:3]
	s_lshl_b64 s[2:3], s[40:41], 5
	s_add_u32 s2, s91, s2
	s_addc_u32 s3, s68, s3
	global_load_dword v73, v119, s[2:3]
	s_lshl_b64 s[2:3], s[30:31], 5
	s_add_u32 s2, s91, s2
	s_addc_u32 s3, s68, s3
	global_load_dword v70, v119, s[2:3]
	s_lshl_b64 s[2:3], s[36:37], 5
	s_add_u32 s2, s91, s2
	s_addc_u32 s3, s68, s3
	s_lshl_b64 s[0:1], s[0:1], 5
	s_add_u32 s0, s91, s0
	s_addc_u32 s1, s68, s1
	global_load_dword v71, v119, s[2:3]
	global_load_dword v68, v119, s[0:1]
	s_lshl_b64 s[0:1], s[72:73], 5
	s_add_u32 s0, s91, s0
	s_addc_u32 s1, s68, s1
	global_load_dword v0, v[0:1], off
	global_load_dword v69, v119, s[0:1]
	s_lshl_b64 s[0:1], s[52:53], 5
	s_add_u32 s0, s91, s0
	s_addc_u32 s1, s68, s1
	global_load_dword v1, v[2:3], off
	global_load_dword v66, v119, s[0:1]
	s_lshl_b64 s[0:1], s[56:57], 5
	s_add_u32 s0, s91, s0
	v_lshl_add_u64 v[2:3], v[4:5], 2, s[50:51]
	s_addc_u32 s1, s68, s1
	global_load_dword v2, v[2:3], off
	v_lshl_add_u64 v[4:5], v[6:7], 2, s[50:51]
	global_load_dword v67, v119, s[0:1]
	s_lshl_b64 s[0:1], s[96:97], 5
	s_add_u32 s0, s91, s0
	s_addc_u32 s1, s68, s1
	global_load_dword v3, v[4:5], off
	global_load_dword v62, v119, s[0:1]
	s_lshl_b64 s[0:1], vcc, 5
	s_add_u32 s0, s91, s0
	v_lshl_add_u64 v[4:5], v[8:9], 2, s[50:51]
	s_addc_u32 s1, s68, s1
	global_load_dword v4, v[4:5], off
	v_lshl_add_u64 v[6:7], v[10:11], 2, s[50:51]
	global_load_dword v63, v119, s[0:1]
	s_lshl_b64 s[0:1], s[92:93], 5
	s_add_u32 s0, s91, s0
	s_addc_u32 s1, s68, s1
	global_load_dword v5, v[6:7], off
	global_load_dword v60, v119, s[0:1]
	s_lshl_b64 s[0:1], s[94:95], 5
	s_add_u32 s0, s91, s0
	v_lshl_add_u64 v[6:7], v[12:13], 2, s[50:51]
	v_lshl_add_u64 v[8:9], v[14:15], 2, s[50:51]
	s_addc_u32 s1, s68, s1
	global_load_dword v6, v[6:7], off
	v_lshl_add_u64 v[10:11], v[18:19], 2, s[50:51]
	global_load_dword v61, v119, s[0:1]
	global_load_dword v7, v[8:9], off
	v_lshl_add_u64 v[8:9], v[16:17], 2, s[50:51]
	global_load_dword v8, v[8:9], off
	v_lshl_add_u64 v[12:13], v[22:23], 2, s[50:51]
	global_load_dword v9, v[10:11], off
	v_lshl_add_u64 v[10:11], v[20:21], 2, s[50:51]
	global_load_dword v10, v[10:11], off
	v_lshl_add_u64 v[14:15], v[42:43], 2, s[50:51]
	global_load_dword v11, v[12:13], off
	v_lshl_add_u64 v[12:13], v[38:39], 2, s[50:51]
	global_load_dword v12, v[12:13], off
	v_lshl_add_u64 v[16:17], v[46:47], 2, s[50:51]
	global_load_dword v13, v[14:15], off
	v_lshl_add_u64 v[14:15], v[40:41], 2, s[50:51]
	global_load_dword v14, v[14:15], off
	s_lshl_b32 s0, s69, 2
	global_load_dword v15, v[16:17], off
	v_lshlrev_b32_e32 v16, 2, v24
	v_mov_b32_e32 v17, v119
	v_add_u32_e32 v18, s89, v199
	s_add_i32 s2, s0, 0
	s_lshl_b32 s92, s80, 1
	s_mov_b32 s93, s85
	v_lshl_add_u64 v[40:41], s[4:5], 0, v[16:17]
	s_mov_b64 s[0:1], 0x1000
	v_lshl_add_u32 v25, v113, 1, s88
	s_add_i32 s2, s2, 0x19e00
	v_lshl_add_u64 v[38:39], v[138:139], 0, s[92:93]
	v_lshl_add_u64 v[42:43], v[40:41], 0, s[0:1]
	v_lshl_add_u64 v[44:45], s[16:17], 0, v[16:17]
	v_lshl_add_u64 v[46:47], s[18:19], 0, v[16:17]
	v_lshl_add_u64 v[48:49], v[150:151], 0, s[92:93]
	v_lshl_add_u64 v[50:51], v[152:153], 0, s[92:93]
	v_lshl_add_u64 v[52:53], v[154:155], 0, s[92:93]
	v_lshl_add_u64 v[54:55], v[156:157], 0, s[92:93]
	v_lshl_add_u64 v[56:57], v[158:159], 0, s[92:93]
	v_add_u32_e32 v85, v18, v200
	s_add_i32 s3, s88, 0x800
	s_add_i32 s4, s88, 0x1400
	global_load_dword v120, v[40:41], off
	global_load_dword v224, v[40:41], off offset:2048
	global_load_dword v226, v[46:47], off
	global_load_dword v112, v[44:45], off
	global_load_dword v116, v[42:43], off
	s_waitcnt vmcnt(0)
	v_lshlrev_b32_e32 v26, 16, v26
	v_lshlrev_b32_e32 v27, 16, v27
	v_lshlrev_b32_e32 v28, 16, v28
	v_lshlrev_b32_e32 v29, 16, v29
	v_lshlrev_b32_e32 v30, 16, v30
	v_lshlrev_b32_e32 v31, 16, v31
	v_lshlrev_b32_e32 v32, 16, v32
	v_lshlrev_b32_e32 v33, 16, v33
	v_lshlrev_b32_e32 v34, 16, v34
	v_lshlrev_b32_e32 v35, 16, v35
	v_lshlrev_b32_e32 v58, 16, v58
	v_lshlrev_b32_e32 v59, 16, v59
	v_lshlrev_b32_e32 v64, 16, v64
	v_lshlrev_b32_e32 v65, 16, v65
	v_lshlrev_b32_e32 v76, 16, v76
	v_lshlrev_b32_e32 v77, 16, v77
	s_branch .LBB0_1422
